# P4 in-proj GEMM: 5th-round tiles moved from rope-column CUs to plain-column CUs (balance epilogue cost); on top of final5
# baseline (speedup 1.0000x reference)
; DEVI bool tile_next(int i, int nM, int nN, int& pm, int& pn) {
;   const int nwg = nM * nN; const long Lx = (long)i * gridDim.x + blockIdx.x; if (Lx >= nwg) return false;
;   int wgid = (int)Lx; { const int q = nwg / 8, r = nwg % 8, xcd = wgid % 8, off = wgid / 8; wgid = (xcd < r ? xcd * (q + 1) : r * (q + 1) + (xcd - r) * q) + off; }
;   constexpr int WGM = 4; const int nig = WGM * nN, gid = wgid / nig, fm = gid * WGM, gsz = (nM - fm) < WGM ? (nM - fm) : WGM;
;   pm = fm + ((wgid % nig) % gsz); pn = (wgid % nig) / gsz; return true;
; template <class Epi>
; DEVI void gemm_phase(const Params& p, const u16* __restrict__ A, const u16* __restrict__ Bt, const int M, const int N, const int K, const int Msplit, const Epi& epi) {
;     ...
;   auto unit_next = [&](const int i, int& pm_, int& pn_, int& kt0_, int& ntl_) -> bool {
;     kt0_ = 0; ntl_ = ntT;
;     if (tile_next(i, nM, nN, pm_, pn_)) return true;
.LBB0_1096:
	s_add_i32 s56, s18, 1
	s_mul_i32 s11, s56, s3
	v_readlane_b32 s12, v252, 0
	s_cmp_lg_u32 s56, 4
	s_cbranch_scc1 .Lmy_p4map_done
	s_cmpk_eq_u32 s3, 0x100
	s_cbranch_scc0 .Lmy_p4map_done
	s_and_b32 s14, s12, 3
	s_cmp_eq_u32 s14, 3
	s_cbranch_scc0 .Lmy_p4map_x2
	s_cmpk_lt_u32 s12, 0x80
	s_cbranch_scc0 .Lmy_p4map_done
	s_xor_b32 s12, s12, 64
	s_branch .Lmy_p4map_done
.Lmy_p4map_x2:
	s_cmp_eq_u32 s14, 2
	s_cbranch_scc0 .Lmy_p4map_done
	s_lshr_b32 s14, s12, 5
	s_cmp_eq_u32 s14, 1
	s_cselect_b32 s15, 1, 0
	s_cmp_eq_u32 s14, 4
	s_cselect_b32 s14, 1, 0
	s_or_b32 s14, s14, s15
	s_cmp_lg_u32 s14, 0
	s_cbranch_scc0 .Lmy_p4map_done
	s_xor_b32 s12, s12, 0xa0
.Lmy_p4map_done:
	s_mul_hi_u32 s10, s56, s3
	s_add_u32 s14, s11, s12
	s_addc_u32 s15, s10, 0
	v_mov_b64_e32 v[0:1], 0x440
	v_cmp_lt_u64_e64 s[12:13], s[14:15], v[0:1]
	v_mov_b64_e32 v[0:1], 0x43f
	v_cmp_gt_u64_e64 s[10:11], s[14:15], v[0:1]
	s_and_b64 vcc, exec, s[10:11]
	s_cbranch_vccnz .LBB0_1098
	s_lshr_b32 s15, s14, 3
	s_and_b32 s14, s14, 7
	s_mulk_i32 s14, 0x88
	s_add_i32 s14, s14, s15
	s_lshr_b32 s15, s14, 3
	s_and_b32 s19, s15, 0xfc
	s_sub_i32 s15, 0x88, s19
	s_min_u32 s20, s15, 4
	v_cvt_f32_ubyte0_e32 v1, s20
	v_rcp_iflag_f32_e32 v2, v1
	s_and_b32 s21, s14, 31
	v_cvt_f32_ubyte0_e32 v0, s21
	v_mul_f32_e32 v2, v0, v2
	v_trunc_f32_e32 v2, v2
	v_fma_f32 v0, -v2, v1, v0
	v_cvt_u32_f32_e32 v2, v2
	v_cmp_ge_f32_e64 s[14:15], |v0|, v1
	s_cmp_lg_u64 s[14:15], 0
	v_readfirstlane_b32 s22, v2
	s_addc_u32 s14, s22, 0
	s_and_b32 s57, s14, 0xff
	s_mul_i32 s14, s14, s20
	s_sub_i32 s14, s21, s14
	s_and_b32 s14, s14, 0xff
	s_add_i32 s62, s19, s14
